# one static s_setprio 1 for waves 0-3 at kernel entry (timing only)
# speedup vs baseline: 1.0280x; 1.0000x over previous
_Z8mega_fwd6Params:
	s_load_dwordx4 s[28:31], s[0:1], 0xc0
	s_load_dword s56, s[0:1], 0xd0
	v_and_b32_e32 v1, 0x3ff, v0
	s_add_u32 s38, s0, 0xc8
	v_readfirstlane_b32 s3, v1
	s_addc_u32 s39, s1, 0
	s_and_b32 s33, s3, 0xffffffc0
	s_cmp_lt_u32 s33, 0x100
	s_cbranch_scc0 .Lmy_prio_done
	s_setprio 1
.Lmy_prio_done:
	v_mbcnt_lo_u32_b32 v2, -1, 0
	v_mbcnt_hi_u32_b32 v2, -1, v2
	v_writelane_b32 v252, s3, 0
	v_or_b32_e32 v2, s33, v2
	v_cmp_gt_i32_e32 vcc, 4, v2
	s_and_saveexec_b64 s[4:5], vcc
	v_lshl_add_u32 v2, v2, 2, 0
	v_add_u32_e32 v2, 0x20000, v2
	v_mov_b32_e32 v3, 0
	ds_write_b32 v2, v3
	s_or_b64 exec, exec, s[4:5]
	s_waitcnt lgkmcnt(0)
	s_barrier
	s_getreg_b32 s3, hwreg(20, 0, 4)
	v_mbcnt_lo_u32_b32 v2, -1, 0
	v_mbcnt_hi_u32_b32 v2, -1, v2
	s_add_u32 s36, s28, 0xe20c000
	v_or_b32_e32 v2, s33, v2
	s_addc_u32 s37, s29, 0
	v_cmp_eq_u32_e32 vcc, 0, v2
	s_and_saveexec_b64 s[4:5], vcc
	s_cbranch_execz .LBB0_5
	s_mov_b64 s[6:7], exec
	v_mbcnt_lo_u32_b32 v2, s6, 0
	v_mbcnt_hi_u32_b32 v2, s7, v2
	v_cmp_eq_u32_e32 vcc, 0, v2
	s_and_b64 s[8:9], exec, vcc
	s_mov_b64 exec, s[8:9]
	s_cbranch_execz .LBB0_5
	s_lshl_b32 s3, s3, 8
	s_and_b32 s3, s3, 0xf00
	s_bcnt1_i32_b64 s6, s[6:7]
	v_mov_b32_e32 v2, s3
	v_mov_b32_e32 v3, s6
	global_atomic_add v2, v3, s[36:37] offset:1024
